# branch-projection epilogue: gate bytes of the second half requested together with the first half's (their memory latency was exposed once more per unit pass)
# baseline (speedup 1.0000x reference)
; __device__ __forceinline__ float bflo(unsigned w) { return __uint_as_float(w << 16); }
; __device__ __forceinline__ float bfhi(unsigned w) { return __uint_as_float(w & 0xffff0000u); }
;   __device__ __forceinline__ void operator()(const f32x4 (&acc)[2][2][4][2], const Unit& u, int wr, int wc, int fr, int fq) const {
;     ...
; #pragma unroll
;       for (int m = 0; m < 4; ++m)
; #pragma unroll
;         for (int bj = 0; bj < 2; ++bj) {
;           const size_t o = (size_t)(u.pm * 256 + ai * 128 + wr * 64 + m * 16 + fr) * 1024 + u.pn * 256 + bj * 128 + wc * 32 + 8 * fq;
;           float v[8];
; #pragma unroll
;           for (int e = 0; e < 8; ++e) v[e] = (float)((gw[m][bj][e >> 2] >> (8 * (e & 3))) & 0xffu) * (1.f / 255.f) * acc[ai][bj][m][e >> 2][e & 3];
; #pragma unroll
;           for (int e = 0; e < 4; ++e) { v[2 * e] += bflo(pw[m][bj][e]); v[2 * e + 1] += bfhi(pw[m][bj][e]); }
;           u32x4 w;
; #pragma unroll
;           for (int e = 0; e < 4; ++e) w[e] = cvt_pk_bf16(v[2 * e], v[2 * e + 1]);
;           *(u32x4*)(mrg + o) = w;
;         }
.LBB0_3528:
	s_waitcnt vmcnt(0)
	v_mov_b32_e32 v110, v222
	v_mov_b32_e32 v111, v223
	v_mov_b32_e32 v108, v224
	v_mov_b32_e32 v109, v225
	v_mov_b32_e32 v104, v226
	v_mov_b32_e32 v105, v227
	v_mov_b32_e32 v102, v228
	v_mov_b32_e32 v103, v229
	v_mov_b32_e32 v100, v230
	v_mov_b32_e32 v101, v231
	v_mov_b32_e32 v98, v232
	v_mov_b32_e32 v99, v233
	v_mov_b32_e32 v96, v234
	v_mov_b32_e32 v97, v235
	v_mov_b32_e32 v94, v236
	v_mov_b32_e32 v95, v237
	v_cvt_f32_ubyte0_e32 v112, v110
	v_mul_f32_e32 v112, 0x3b808081, v112
	v_cvt_f32_ubyte1_e32 v113, v110
	v_lshlrev_b32_e32 v118, 16, v130
	v_mul_f32_e32 v113, 0x3b808081, v113
	v_cvt_f32_ubyte2_e32 v114, v110
	v_fmac_f32_e32 v118, v62, v112
	v_and_b32_e32 v62, 0xffff0000, v130
	v_mul_f32_e32 v114, 0x3b808081, v114
	v_cvt_f32_ubyte3_e32 v110, v110
	v_fmac_f32_e32 v62, v63, v113
	v_lshlrev_b32_e32 v63, 16, v131
	v_mul_f32_e32 v110, 0x3b808081, v110
	v_cvt_f32_ubyte0_e32 v115, v111
	v_cvt_f32_ubyte1_e32 v116, v111
	v_fmac_f32_e32 v63, v64, v114
	v_and_b32_e32 v64, 0xffff0000, v131
	v_mul_f32_e32 v115, 0x3b808081, v115
	v_mul_f32_e32 v116, 0x3b808081, v116
	v_fmac_f32_e32 v64, v65, v110
	v_lshlrev_b32_e32 v65, 16, v132
	v_and_b32_e32 v110, 0xffff0000, v132
	v_fmac_f32_e32 v65, v58, v115
	v_fmac_f32_e32 v110, v59, v116
	v_cvt_pk_bf16_f32 v58, v118, v62
	v_cvt_pk_bf16_f32 v59, v63, v64
	v_lshlrev_b64 v[62:63], 11, v[106:107]
	v_lshl_add_u64 v[62:63], s[4:5], 0, v[62:63]
	v_readlane_b32 s0, v255, 20
	v_lshl_add_u64 v[62:63], v[62:63], 0, s[20:21]
	v_readlane_b32 s1, v255, 21
	v_cvt_f32_ubyte2_e32 v117, v111
	v_cvt_f32_ubyte3_e32 v111, v111
	v_lshl_add_u64 v[62:63], v[62:63], 0, s[0:1]
	v_mul_f32_e32 v117, 0x3b808081, v117
	v_mul_f32_e32 v111, 0x3b808081, v111
	v_lshlrev_b32_e32 v112, 16, v133
	v_and_b32_e32 v113, 0xffff0000, v133
	v_lshl_add_u64 v[62:63], v[62:63], 0, v[16:17]
	v_fmac_f32_e32 v112, v60, v117
	v_fmac_f32_e32 v113, v61, v111
	v_cvt_pk_bf16_f32 v60, v65, v110
	v_cvt_pk_bf16_f32 v61, v112, v113
	global_store_dwordx4 v[62:63], v[58:61], off
	v_cvt_f32_ubyte0_e32 v64, v109
	v_cvt_f32_ubyte1_e32 v65, v109
	v_cvt_f32_ubyte0_e32 v58, v108
	v_mul_f32_e32 v58, 0x3b808081, v58
	v_cvt_f32_ubyte1_e32 v59, v108
	v_cvt_f32_ubyte2_e32 v60, v108
	v_cvt_f32_ubyte3_e32 v61, v108
	v_lshlrev_b32_e32 v108, 16, v90
	v_mul_f32_e32 v59, 0x3b808081, v59
	v_fmac_f32_e32 v108, v54, v58
	v_and_b32_e32 v54, 0xffff0000, v90
	v_mul_f32_e32 v60, 0x3b808081, v60
	v_fmac_f32_e32 v54, v55, v59
	v_lshlrev_b32_e32 v55, 16, v91
	v_mul_f32_e32 v61, 0x3b808081, v61
	v_fmac_f32_e32 v55, v56, v60
	v_and_b32_e32 v56, 0xffff0000, v91
	v_mul_f32_e32 v64, 0x3b808081, v64
	v_mul_f32_e32 v65, 0x3b808081, v65
	v_cvt_f32_ubyte2_e32 v106, v109
	v_cvt_f32_ubyte3_e32 v107, v109
	v_fmac_f32_e32 v56, v57, v61
	v_lshlrev_b32_e32 v57, 16, v92
	v_and_b32_e32 v58, 0xffff0000, v92
	v_mul_f32_e32 v106, 0x3b808081, v106
	v_mul_f32_e32 v107, 0x3b808081, v107
	v_fmac_f32_e32 v57, v50, v64
	v_fmac_f32_e32 v58, v51, v65
	v_lshlrev_b32_e32 v59, 16, v93
	v_and_b32_e32 v60, 0xffff0000, v93
	v_cvt_pk_bf16_f32 v50, v108, v54
	v_cvt_pk_bf16_f32 v51, v55, v56
	v_fmac_f32_e32 v59, v52, v106
	v_fmac_f32_e32 v60, v53, v107
	v_cvt_pk_bf16_f32 v52, v57, v58
	v_cvt_pk_bf16_f32 v53, v59, v60
	global_store_dwordx4 v[62:63], v[50:53], off offset:256
	v_lshlrev_b32_e32 v59, 16, v82
	v_cvt_f32_ubyte3_e32 v54, v104
	v_cvt_f32_ubyte0_e32 v51, v104
	v_mul_f32_e32 v51, 0x3b808081, v51
	v_cvt_f32_ubyte1_e32 v52, v104
	v_mul_f32_e32 v52, 0x3b808081, v52
	v_cvt_f32_ubyte2_e32 v53, v104
	v_fmac_f32_e32 v59, v46, v51
	v_and_b32_e32 v46, 0xffff0000, v82
	v_mul_f32_e32 v53, 0x3b808081, v53
	v_fmac_f32_e32 v46, v47, v52
	v_lshlrev_b32_e32 v47, 16, v83
	v_add_u32_e32 v50, 0x90, v178
	v_mul_f32_e32 v54, 0x3b808081, v54
	v_cvt_f32_ubyte0_e32 v55, v105
	v_cvt_f32_ubyte1_e32 v56, v105
	v_fmac_f32_e32 v47, v48, v53
	v_and_b32_e32 v48, 0xffff0000, v83
	v_mul_f32_e32 v55, 0x3b808081, v55
	v_mul_f32_e32 v56, 0x3b808081, v56
	v_fmac_f32_e32 v48, v49, v54
	v_lshlrev_b32_e32 v49, 16, v84
	v_and_b32_e32 v52, 0xffff0000, v84
	v_ashrrev_i32_e32 v51, 31, v50
	v_fmac_f32_e32 v49, v42, v55
	v_fmac_f32_e32 v52, v43, v56
	v_cvt_pk_bf16_f32 v42, v59, v46
	v_cvt_pk_bf16_f32 v43, v47, v48
	v_lshlrev_b64 v[46:47], 11, v[50:51]
	v_lshl_add_u64 v[46:47], s[4:5], 0, v[46:47]
	v_lshl_add_u64 v[46:47], v[46:47], 0, s[20:21]
	v_cvt_f32_ubyte2_e32 v57, v105
	v_cvt_f32_ubyte3_e32 v58, v105
	v_lshl_add_u64 v[46:47], v[46:47], 0, s[0:1]
	v_mul_f32_e32 v57, 0x3b808081, v57
	v_mul_f32_e32 v58, 0x3b808081, v58
	v_lshlrev_b32_e32 v53, 16, v85
	v_and_b32_e32 v54, 0xffff0000, v85
	v_lshl_add_u64 v[46:47], v[46:47], 0, v[16:17]
	v_fmac_f32_e32 v53, v44, v57
	v_fmac_f32_e32 v54, v45, v58
	v_cvt_pk_bf16_f32 v44, v49, v52
	v_cvt_pk_bf16_f32 v45, v53, v54
	global_store_dwordx4 v[46:47], v[42:45], off
	v_lshlrev_b32_e32 v52, 16, v86
	v_cvt_f32_ubyte0_e32 v48, v103
	v_cvt_f32_ubyte0_e32 v42, v102
	v_mul_f32_e32 v42, 0x3b808081, v42
	v_cvt_f32_ubyte1_e32 v43, v102
	v_mul_f32_e32 v43, 0x3b808081, v43
	v_cvt_f32_ubyte2_e32 v44, v102
	v_fmac_f32_e32 v52, v38, v42
	v_and_b32_e32 v38, 0xffff0000, v86
	v_mul_f32_e32 v44, 0x3b808081, v44
	v_cvt_f32_ubyte3_e32 v45, v102
	v_fmac_f32_e32 v38, v39, v43
	v_lshlrev_b32_e32 v39, 16, v87
	v_mul_f32_e32 v45, 0x3b808081, v45
	v_cvt_f32_ubyte1_e32 v49, v103
	v_fmac_f32_e32 v39, v40, v44
	v_and_b32_e32 v40, 0xffff0000, v87
	v_mul_f32_e32 v48, 0x3b808081, v48
	v_mul_f32_e32 v49, 0x3b808081, v49
	v_cvt_f32_ubyte2_e32 v50, v103
	v_cvt_f32_ubyte3_e32 v51, v103
	v_fmac_f32_e32 v40, v41, v45
	v_lshlrev_b32_e32 v41, 16, v88
	v_and_b32_e32 v42, 0xffff0000, v88
	v_mul_f32_e32 v50, 0x3b808081, v50
; __device__ __forceinline__ float bflo(unsigned w) { return __uint_as_float(w << 16); }
; __device__ __forceinline__ float bfhi(unsigned w) { return __uint_as_float(w & 0xffff0000u); }
; template <class Epi>
; __device__ __forceinline__ void gemm_phase(LAS unsigned char* lds, const Gemm g, const StaticOrder& S, const Epi& E) {
;     ...
;     if (!has_next) break;
; #pragma unroll
;     for (int a = 0; a < 2; ++a)
; #pragma unroll
;       for (int b = 0; b < 2; ++b)
; #pragma unroll
;         for (int m = 0; m < 4; ++m)
; #pragma unroll
;           for (int n = 0; n < 2; ++n) acc[a][b][m][n] = (f32x4){0.f, 0.f, 0.f, 0.f};
;     cur = nxt; cA = nA; cB = nB; ++ui;
;   __device__ __forceinline__ void operator()(const f32x4 (&acc)[2][2][4][2], const Unit& u, int wr, int wc, int fr, int fq) const {
;     ...
; #pragma unroll
;       for (int m = 0; m < 4; ++m)
; #pragma unroll
;         for (int bj = 0; bj < 2; ++bj) {
;           const size_t o = (size_t)(u.pm * 256 + ai * 128 + wr * 64 + m * 16 + fr) * 1024 + u.pn * 256 + bj * 128 + wc * 32 + 8 * fq;
;           float v[8];
; #pragma unroll
;           for (int e = 0; e < 8; ++e) v[e] = (float)((gw[m][bj][e >> 2] >> (8 * (e & 3))) & 0xffu) * (1.f / 255.f) * acc[ai][bj][m][e >> 2][e & 3];
; #pragma unroll
;           for (int e = 0; e < 4; ++e) { v[2 * e] += bflo(pw[m][bj][e]); v[2 * e + 1] += bfhi(pw[m][bj][e]); }
;           u32x4 w;
; #pragma unroll
;           for (int e = 0; e < 4; ++e) w[e] = cvt_pk_bf16(v[2 * e], v[2 * e + 1]);
;           *(u32x4*)(mrg + o) = w;
;         }
	v_mul_f32_e32 v51, 0x3b808081, v51
	v_fmac_f32_e32 v41, v34, v48
	v_fmac_f32_e32 v42, v35, v49
	v_lshlrev_b32_e32 v43, 16, v89
	v_and_b32_e32 v44, 0xffff0000, v89
	v_cvt_pk_bf16_f32 v34, v52, v38
	v_cvt_pk_bf16_f32 v35, v39, v40
	v_fmac_f32_e32 v43, v36, v50
	v_fmac_f32_e32 v44, v37, v51
	v_cvt_pk_bf16_f32 v36, v41, v42
	v_cvt_pk_bf16_f32 v37, v43, v44
	global_store_dwordx4 v[46:47], v[34:37], off offset:256
	v_lshlrev_b32_e32 v43, 16, v74
	v_cvt_f32_ubyte3_e32 v38, v100
	v_cvt_f32_ubyte0_e32 v35, v100
	v_mul_f32_e32 v35, 0x3b808081, v35
	v_cvt_f32_ubyte1_e32 v36, v100
	v_mul_f32_e32 v36, 0x3b808081, v36
	v_cvt_f32_ubyte2_e32 v37, v100
	v_fmac_f32_e32 v43, v30, v35
	v_and_b32_e32 v30, 0xffff0000, v74
	v_mul_f32_e32 v37, 0x3b808081, v37
	v_fmac_f32_e32 v30, v31, v36
	v_lshlrev_b32_e32 v31, 16, v75
	v_add_u32_e32 v34, 0xa0, v178
	v_mul_f32_e32 v38, 0x3b808081, v38
	v_cvt_f32_ubyte0_e32 v39, v101
	v_cvt_f32_ubyte1_e32 v40, v101
	v_fmac_f32_e32 v31, v32, v37
	v_and_b32_e32 v32, 0xffff0000, v75
	v_mul_f32_e32 v39, 0x3b808081, v39
	v_mul_f32_e32 v40, 0x3b808081, v40
	v_fmac_f32_e32 v32, v33, v38
	v_lshlrev_b32_e32 v33, 16, v76
	v_and_b32_e32 v36, 0xffff0000, v76
	v_ashrrev_i32_e32 v35, 31, v34
	v_fmac_f32_e32 v33, v26, v39
	v_fmac_f32_e32 v36, v27, v40
	v_cvt_pk_bf16_f32 v26, v43, v30
	v_cvt_pk_bf16_f32 v27, v31, v32
	v_lshlrev_b64 v[30:31], 11, v[34:35]
	v_lshl_add_u64 v[30:31], s[4:5], 0, v[30:31]
	v_lshl_add_u64 v[30:31], v[30:31], 0, s[20:21]
	v_cvt_f32_ubyte2_e32 v41, v101
	v_cvt_f32_ubyte3_e32 v42, v101
	v_lshl_add_u64 v[30:31], v[30:31], 0, s[0:1]
	v_mul_f32_e32 v41, 0x3b808081, v41
	v_mul_f32_e32 v42, 0x3b808081, v42
	v_lshlrev_b32_e32 v37, 16, v77
	v_and_b32_e32 v38, 0xffff0000, v77
	v_lshl_add_u64 v[30:31], v[30:31], 0, v[16:17]
	v_fmac_f32_e32 v37, v28, v41
	v_fmac_f32_e32 v38, v29, v42
	v_cvt_pk_bf16_f32 v28, v33, v36
	v_cvt_pk_bf16_f32 v29, v37, v38
	global_store_dwordx4 v[30:31], v[26:29], off
	v_lshlrev_b32_e32 v36, 16, v78
	v_cvt_f32_ubyte0_e32 v32, v99
	v_cvt_f32_ubyte0_e32 v26, v98
	v_mul_f32_e32 v26, 0x3b808081, v26
	v_cvt_f32_ubyte1_e32 v27, v98
	v_mul_f32_e32 v27, 0x3b808081, v27
	v_cvt_f32_ubyte2_e32 v28, v98
	v_fmac_f32_e32 v36, v22, v26
	v_and_b32_e32 v22, 0xffff0000, v78
	v_mul_f32_e32 v28, 0x3b808081, v28
	v_cvt_f32_ubyte3_e32 v29, v98
	v_fmac_f32_e32 v22, v23, v27
	v_lshlrev_b32_e32 v23, 16, v79
	v_mul_f32_e32 v29, 0x3b808081, v29
	v_cvt_f32_ubyte1_e32 v33, v99
	v_fmac_f32_e32 v23, v24, v28
	v_and_b32_e32 v24, 0xffff0000, v79
	v_mul_f32_e32 v32, 0x3b808081, v32
	v_mul_f32_e32 v33, 0x3b808081, v33
	v_cvt_f32_ubyte2_e32 v34, v99
	v_cvt_f32_ubyte3_e32 v35, v99
	v_fmac_f32_e32 v24, v25, v29
	v_lshlrev_b32_e32 v25, 16, v80
	v_and_b32_e32 v26, 0xffff0000, v80
	v_mul_f32_e32 v34, 0x3b808081, v34
	v_mul_f32_e32 v35, 0x3b808081, v35
	v_fmac_f32_e32 v25, v18, v32
	v_fmac_f32_e32 v26, v19, v33
	v_lshlrev_b32_e32 v27, 16, v81
	v_and_b32_e32 v28, 0xffff0000, v81
	v_cvt_pk_bf16_f32 v18, v36, v22
	v_cvt_pk_bf16_f32 v19, v23, v24
	v_fmac_f32_e32 v27, v20, v34
	v_fmac_f32_e32 v28, v21, v35
	v_cvt_pk_bf16_f32 v20, v25, v26
	v_cvt_pk_bf16_f32 v21, v27, v28
	global_store_dwordx4 v[30:31], v[18:21], off offset:256
	v_lshlrev_b32_e32 v27, 16, v66
	v_cvt_f32_ubyte3_e32 v22, v96
	v_cvt_f32_ubyte0_e32 v19, v96
	v_mul_f32_e32 v19, 0x3b808081, v19
	v_cvt_f32_ubyte1_e32 v20, v96
	v_mul_f32_e32 v20, 0x3b808081, v20
	v_cvt_f32_ubyte2_e32 v21, v96
	v_fmac_f32_e32 v27, v12, v19
	v_and_b32_e32 v12, 0xffff0000, v66
	v_mul_f32_e32 v21, 0x3b808081, v21
	v_fmac_f32_e32 v12, v13, v20
	v_lshlrev_b32_e32 v13, 16, v67
	v_add_u32_e32 v18, 0xb0, v178
	v_mul_f32_e32 v22, 0x3b808081, v22
	v_cvt_f32_ubyte0_e32 v23, v97
	v_cvt_f32_ubyte1_e32 v24, v97
	v_fmac_f32_e32 v13, v14, v21
	v_and_b32_e32 v14, 0xffff0000, v67
	v_mul_f32_e32 v23, 0x3b808081, v23
	v_mul_f32_e32 v24, 0x3b808081, v24
	v_fmac_f32_e32 v14, v15, v22
	v_lshlrev_b32_e32 v15, 16, v68
	v_and_b32_e32 v20, 0xffff0000, v68
	v_ashrrev_i32_e32 v19, 31, v18
	v_fmac_f32_e32 v15, v8, v23
	v_fmac_f32_e32 v20, v9, v24
	v_cvt_pk_bf16_f32 v8, v27, v12
	v_cvt_pk_bf16_f32 v9, v13, v14
	v_lshlrev_b64 v[12:13], 11, v[18:19]
	v_lshl_add_u64 v[12:13], s[4:5], 0, v[12:13]
	v_lshl_add_u64 v[12:13], v[12:13], 0, s[20:21]
	v_cvt_f32_ubyte2_e32 v25, v97
	v_cvt_f32_ubyte3_e32 v26, v97
	v_lshl_add_u64 v[12:13], v[12:13], 0, s[0:1]
	v_mul_f32_e32 v25, 0x3b808081, v25
	v_mul_f32_e32 v26, 0x3b808081, v26
	v_lshlrev_b32_e32 v21, 16, v69
	v_and_b32_e32 v22, 0xffff0000, v69
	v_lshl_add_u64 v[12:13], v[12:13], 0, v[16:17]
	v_fmac_f32_e32 v21, v10, v25
	v_fmac_f32_e32 v22, v11, v26
	v_cvt_pk_bf16_f32 v10, v15, v20
	v_cvt_pk_bf16_f32 v11, v21, v22
	global_store_dwordx4 v[12:13], v[8:11], off
	v_lshlrev_b32_e32 v20, 16, v70
	v_cvt_f32_ubyte0_e32 v14, v95
	v_cvt_f32_ubyte0_e32 v8, v94
	v_mul_f32_e32 v8, 0x3b808081, v8
	v_cvt_f32_ubyte1_e32 v9, v94
	v_mul_f32_e32 v9, 0x3b808081, v9
	v_cvt_f32_ubyte2_e32 v10, v94
	v_fmac_f32_e32 v20, v4, v8
	v_and_b32_e32 v4, 0xffff0000, v70
	v_mul_f32_e32 v10, 0x3b808081, v10
	v_cvt_f32_ubyte3_e32 v11, v94
	v_fmac_f32_e32 v4, v5, v9
	v_lshlrev_b32_e32 v5, 16, v71
	v_mul_f32_e32 v11, 0x3b808081, v11
	v_cvt_f32_ubyte1_e32 v15, v95
	v_cvt_f32_ubyte2_e32 v18, v95
	v_cvt_f32_ubyte3_e32 v19, v95
	v_fmac_f32_e32 v5, v6, v10
	v_and_b32_e32 v6, 0xffff0000, v71
	v_mul_f32_e32 v14, 0x3b808081, v14
	v_mul_f32_e32 v15, 0x3b808081, v15
	v_mul_f32_e32 v18, 0x3b808081, v18
	v_mul_f32_e32 v19, 0x3b808081, v19
	v_fmac_f32_e32 v6, v7, v11
	v_lshlrev_b32_e32 v7, 16, v72
	v_and_b32_e32 v8, 0xffff0000, v72
	v_lshlrev_b32_e32 v9, 16, v73
	v_and_b32_e32 v10, 0xffff0000, v73
	s_and_b64 vcc, exec, s[10:11]
	s_mov_b32 s46, s6
	s_mov_b32 s47, s8
	s_mov_b32 s48, s45
	s_mov_b64 s[20:21], s[14:15]
	s_mov_b64 s[22:23], s[12:13]
	v_fmac_f32_e32 v7, v0, v14
	v_fmac_f32_e32 v8, v1, v15
	v_fmac_f32_e32 v9, v2, v18
	v_fmac_f32_e32 v10, v3, v19
	v_cvt_pk_bf16_f32 v0, v20, v4
	v_cvt_pk_bf16_f32 v1, v5, v6
	v_cvt_pk_bf16_f32 v2, v7, v8
	v_cvt_pk_bf16_f32 v3, v9, v10
	global_store_dwordx4 v[12:13], v[0:3], off offset:256
	s_cbranch_vccnz .LBB0_3576

; #define PG8_STAGE(bufoff, gbase, voff) do { _Pragma("unroll") for (int _i = 0; _i < 2; ++_i) \
;     __builtin_amdgcn_global_load_lds((const unsigned*)((const char*)(gbase) + (voff)[_i]), (LAS unsigned*)(lds + (bufoff) + ldsw + _i * 8192), 16, 0, 0); } while (0)
; #define PG8_LDA(dst, b, h) do { _Pragma("unroll") for (int m = 0; m < 4; ++m) _Pragma("unroll") for (int k = 0; k < 2; ++k) dst[m][k] = *(const LAS bf16x8*)(lds + PG8_SA(b, h) + aoff + m * 2048 + k * 1024); } while (0)
; #define PG8_LDB(dst, b, h) do { _Pragma("unroll") for (int n = 0; n < 2; ++n) _Pragma("unroll") for (int k = 0; k < 2; ++k) dst[n][k] = *(const LAS bf16x8*)(lds + PG8_SB(b, h) + boff + n * 2048 + k * 1024); } while (0)
; #define PG8_MMA(ai, bj, At, Bt) do { __builtin_amdgcn_s_setprio(1); _Pragma("unroll") for (int m = 0; m < 4; ++m) _Pragma("unroll") for (int n = 0; n < 2; ++n) _Pragma("unroll") for (int k = 0; k < 2; ++k) \
;     acc[ai][bj][m][n] = __builtin_amdgcn_mfma_f32_16x16x32_bf16(Bt[n][k], At[m][k], acc[ai][bj][m][n], 0, 0, 0); __builtin_amdgcn_s_setprio(0); } while (0)
; #define PG8_WAIT_V(n) asm volatile("s_waitcnt vmcnt(" #n ")" ::: "memory")
; #define PG8_WAIT_L(n) asm volatile("s_waitcnt lgkmcnt(" #n ")" ::: "memory")
; #define PG8_BAR __builtin_amdgcn_s_barrier()
; #define PG8_SCHED __builtin_amdgcn_sched_barrier(0)
; template <class Epi>
; __device__ __forceinline__ void gemm_phase(LAS unsigned char* lds, const Gemm g, const StaticOrder& S, const Epi& E) {
;     ...
;       PG8_LDB(B0, 0, 0); PG8_SCHED; PG8_LDA(At, 0, 0); PG8_STAGE(PG8_SA(1, 1), a1 + hstepA, voffA);
;       PG8_WAIT_L(8); PG8_BAR; PG8_WAIT_L(0); PG8_MMA(0, 0, At, B0); PG8_BAR; PG8_SCHED;
;       PG8_LDB(B1, 0, 1); PG8_STAGE(PG8_SB(0, 0), b2, voffB);
;       PG8_BAR; PG8_WAIT_L(0); PG8_MMA(0, 1, At, B1); PG8_BAR;
;       PG8_LDA(At, 0, 1); PG8_STAGE(PG8_SA(0, 0), a2, voffA);
;       PG8_BAR; PG8_WAIT_L(0); PG8_MMA(1, 0, At, B0); PG8_BAR; PG8_SCHED;
;       PG8_STAGE(PG8_SB(0, 1), b2 + hstepB, voffB);
;       PG8_WAIT_V(6); PG8_BAR; PG8_MMA(1, 1, At, B1); PG8_BAR;
.LBB0_3542:
	s_add_u32 s20, s0, 0xfffe0080
	s_addc_u32 s21, s1, -1
	s_add_i32 s25, 0, 0x10000
	v_add_u32_e32 v142, s25, v196
	ds_read_b128 v[130:133], v142
	ds_read_b128 v[134:137], v142 offset:1024
	ds_read_b128 v[138:141], v142 offset:2048
	ds_read_b128 v[142:145], v142 offset:3072
	s_cmp_eq_u32 s24, 4
	s_cselect_b32 s23, s13, s21
	s_cselect_b32 s22, s12, s20
	s_cselect_b32 s21, s15, s9
	s_cselect_b32 s20, s14, s7
	v_lshl_add_u64 v[162:163], s[0:1], 0, v[174:175]
	s_add_i32 m0, s34, 0xc000
	ds_read_b128 v[146:149], v204
	ds_read_b128 v[150:153], v204 offset:1024
	ds_read_b128 v[154:157], v204 offset:2048
	ds_read_b128 v[158:161], v204 offset:3072
	ds_read_b128 v[178:181], v204 offset:4096
	ds_read_b128 v[182:185], v204 offset:5120
	ds_read_b128 v[186:189], v204 offset:6144
	ds_read_b128 v[190:193], v204 offset:7168
	global_load_lds_dwordx4 v[162:163], off
	v_lshl_add_u64 v[162:163], s[0:1], 0, v[176:177]
	s_add_i32 m0, s34, 0xe000
	s_nop 0
	global_load_lds_dwordx4 v[162:163], off
	s_waitcnt lgkmcnt(8)
	s_barrier
	s_waitcnt lgkmcnt(0)
	s_setprio 1
	s_waitcnt lgkmcnt(0)
	v_mfma_f32_16x16x32_bf16 v[126:129], v[130:133], v[146:149], v[126:129]
	v_mfma_f32_16x16x32_bf16 v[122:125], v[138:141], v[146:149], v[122:125]
	v_mfma_f32_16x16x32_bf16 v[110:113], v[130:133], v[154:157], v[110:113]
	v_mfma_f32_16x16x32_bf16 v[106:109], v[138:141], v[154:157], v[106:109]
	v_mfma_f32_16x16x32_bf16 v[94:97], v[130:133], v[178:181], v[94:97]
	v_mfma_f32_16x16x32_bf16 v[90:93], v[138:141], v[178:181], v[90:93]
	v_mfma_f32_16x16x32_bf16 v[78:81], v[130:133], v[186:189], v[78:81]
	v_mfma_f32_16x16x32_bf16 v[74:77], v[138:141], v[186:189], v[74:77]
	v_mfma_f32_16x16x32_bf16 v[126:129], v[134:137], v[150:153], v[126:129]
	v_mfma_f32_16x16x32_bf16 v[122:125], v[142:145], v[150:153], v[122:125]
	v_mfma_f32_16x16x32_bf16 v[110:113], v[134:137], v[158:161], v[110:113]
	v_mfma_f32_16x16x32_bf16 v[106:109], v[142:145], v[158:161], v[106:109]
	v_mfma_f32_16x16x32_bf16 v[94:97], v[134:137], v[182:185], v[94:97]
	v_mfma_f32_16x16x32_bf16 v[90:93], v[142:145], v[182:185], v[90:93]
	v_mfma_f32_16x16x32_bf16 v[78:81], v[134:137], v[190:193], v[78:81]
	v_mfma_f32_16x16x32_bf16 v[74:77], v[142:145], v[190:193], v[74:77]
	s_setprio 0
	s_barrier
	s_add_i32 s49, 0, 0x14000
	v_add_u32_e32 v162, s49, v196
	s_add_i32 s25, s25, s31
	ds_read_b128 v[198:201], v162
	ds_read_b128 v[206:209], v162 offset:1024
	ds_read_b128 v[210:213], v162 offset:2048
	ds_read_b128 v[214:217], v162 offset:3072
	v_lshl_add_u64 v[162:163], s[20:21], 0, v[168:169]
	s_mov_b32 m0, s25
	v_lshl_add_u64 v[194:195], s[20:21], 0, v[164:165]
	global_load_lds_dwordx4 v[162:163], off
	s_add_i32 m0, s25, 0x2000
	s_nop 0
	global_load_lds_dwordx4 v[194:195], off
	s_barrier
	s_waitcnt lgkmcnt(0)
	s_setprio 1
	s_waitcnt lgkmcnt(0)
	v_mfma_f32_16x16x32_bf16 v[118:121], v[198:201], v[146:149], v[118:121]
	v_mfma_f32_16x16x32_bf16 v[114:117], v[210:213], v[146:149], v[114:117]
	v_mfma_f32_16x16x32_bf16 v[102:105], v[198:201], v[154:157], v[102:105]
	v_mfma_f32_16x16x32_bf16 v[98:101], v[210:213], v[154:157], v[98:101]
	v_mfma_f32_16x16x32_bf16 v[86:89], v[198:201], v[178:181], v[86:89]
	v_mfma_f32_16x16x32_bf16 v[82:85], v[210:213], v[178:181], v[82:85]
	v_mfma_f32_16x16x32_bf16 v[70:73], v[198:201], v[186:189], v[70:73]
	v_mfma_f32_16x16x32_bf16 v[66:69], v[210:213], v[186:189], v[66:69]
	v_mfma_f32_16x16x32_bf16 v[118:121], v[206:209], v[150:153], v[118:121]
	v_mfma_f32_16x16x32_bf16 v[114:117], v[214:217], v[150:153], v[114:117]
	v_mfma_f32_16x16x32_bf16 v[102:105], v[206:209], v[158:161], v[102:105]
	v_mfma_f32_16x16x32_bf16 v[98:101], v[214:217], v[158:161], v[98:101]
	v_mfma_f32_16x16x32_bf16 v[86:89], v[206:209], v[182:185], v[86:89]
	v_mfma_f32_16x16x32_bf16 v[82:85], v[214:217], v[182:185], v[82:85]
	v_mfma_f32_16x16x32_bf16 v[70:73], v[206:209], v[190:193], v[70:73]
	v_mfma_f32_16x16x32_bf16 v[66:69], v[214:217], v[190:193], v[66:69]
	s_setprio 0
	s_mov_b32 m0, s34
	v_lshl_add_u64 v[218:219], s[22:23], 0, v[170:171]
	s_barrier
	ds_read_b128 v[146:149], v204 offset:16384
	ds_read_b128 v[150:153], v204 offset:17408
	ds_read_b128 v[154:157], v204 offset:18432
	ds_read_b128 v[158:161], v204 offset:19456
	ds_read_b128 v[178:181], v204 offset:20480
	ds_read_b128 v[182:185], v204 offset:21504
	ds_read_b128 v[186:189], v204 offset:22528
	ds_read_b128 v[190:193], v204 offset:23552
	global_load_lds_dwordx4 v[218:219], off
	v_lshl_add_u64 v[220:221], s[22:23], 0, v[166:167]
	s_mov_b32 m0, s35
	s_nop 0
	global_load_lds_dwordx4 v[220:221], off
	s_barrier
	s_waitcnt lgkmcnt(0)
	s_setprio 1
	s_waitcnt lgkmcnt(0)
	v_mfma_f32_16x16x32_bf16 v[62:65], v[130:133], v[146:149], v[62:65]
	v_mfma_f32_16x16x32_bf16 v[58:61], v[138:141], v[146:149], v[58:61]
	v_mfma_f32_16x16x32_bf16 v[46:49], v[130:133], v[154:157], v[46:49]
	v_mfma_f32_16x16x32_bf16 v[42:45], v[138:141], v[154:157], v[42:45]
	v_mfma_f32_16x16x32_bf16 v[30:33], v[130:133], v[178:181], v[30:33]
	v_mfma_f32_16x16x32_bf16 v[26:29], v[138:141], v[178:181], v[26:29]
	v_mfma_f32_16x16x32_bf16 v[12:15], v[130:133], v[186:189], v[12:15]
	v_mfma_f32_16x16x32_bf16 v[8:11], v[138:141], v[186:189], v[8:11]
	v_mfma_f32_16x16x32_bf16 v[62:65], v[134:137], v[150:153], v[62:65]
	v_mfma_f32_16x16x32_bf16 v[58:61], v[142:145], v[150:153], v[58:61]
	v_mfma_f32_16x16x32_bf16 v[46:49], v[134:137], v[158:161], v[46:49]
	v_mfma_f32_16x16x32_bf16 v[42:45], v[142:145], v[158:161], v[42:45]
	v_mfma_f32_16x16x32_bf16 v[30:33], v[134:137], v[182:185], v[30:33]
	v_mfma_f32_16x16x32_bf16 v[26:29], v[142:145], v[182:185], v[26:29]
	v_mfma_f32_16x16x32_bf16 v[12:15], v[134:137], v[190:193], v[12:15]
	v_mfma_f32_16x16x32_bf16 v[8:11], v[142:145], v[190:193], v[8:11]
	s_setprio 0
	s_barrier
; #define PG8_STAGE(bufoff, gbase, voff) do { _Pragma("unroll") for (int _i = 0; _i < 2; ++_i) \
;     __builtin_amdgcn_global_load_lds((const unsigned*)((const char*)(gbase) + (voff)[_i]), (LAS unsigned*)(lds + (bufoff) + ldsw + _i * 8192), 16, 0, 0); } while (0)
; #define PG8_LDA(dst, b, h) do { _Pragma("unroll") for (int m = 0; m < 4; ++m) _Pragma("unroll") for (int k = 0; k < 2; ++k) dst[m][k] = *(const LAS bf16x8*)(lds + PG8_SA(b, h) + aoff + m * 2048 + k * 1024); } while (0)
; #define PG8_LDB(dst, b, h) do { _Pragma("unroll") for (int n = 0; n < 2; ++n) _Pragma("unroll") for (int k = 0; k < 2; ++k) dst[n][k] = *(const LAS bf16x8*)(lds + PG8_SB(b, h) + boff + n * 2048 + k * 1024); } while (0)
; #define PG8_MMA(ai, bj, At, Bt) do { __builtin_amdgcn_s_setprio(1); _Pragma("unroll") for (int m = 0; m < 4; ++m) _Pragma("unroll") for (int n = 0; n < 2; ++n) _Pragma("unroll") for (int k = 0; k < 2; ++k) \
;     acc[ai][bj][m][n] = __builtin_amdgcn_mfma_f32_16x16x32_bf16(Bt[n][k], At[m][k], acc[ai][bj][m][n], 0, 0, 0); __builtin_amdgcn_s_setprio(0); } while (0)
; #define PG8_WAIT_V(n) asm volatile("s_waitcnt vmcnt(" #n ")" ::: "memory")
; #define PG8_WAIT_L(n) asm volatile("s_waitcnt lgkmcnt(" #n ")" ::: "memory")
; #define PG8_BAR __builtin_amdgcn_s_barrier()
; #define PG8_SCHED __builtin_amdgcn_sched_barrier(0)
; template <class Epi>
; __device__ __forceinline__ void gemm_phase(LAS unsigned char* lds, const Gemm g, const StaticOrder& S, const Epi& E) {
;     ...
;       PG8_WAIT_V(6); PG8_BAR; PG8_MMA(1, 1, At, B1); PG8_BAR;
;       PG8_LDB(B0, 1, 0); PG8_SCHED; PG8_LDA(At, 1, 0); PG8_STAGE(PG8_SA(0, 1), a2 + hstepA, voffA);
;       PG8_WAIT_L(8); PG8_BAR; PG8_WAIT_L(0); PG8_MMA(0, 0, At, B0); PG8_BAR; PG8_SCHED;
;       PG8_LDB(B1, 1, 1); PG8_STAGE(PG8_SB(1, 0), b3, voffB);
;       PG8_BAR; PG8_WAIT_L(0); PG8_MMA(0, 1, At, B1); PG8_BAR;
;       PG8_LDA(At, 1, 1); PG8_STAGE(PG8_SA(1, 0), a3, voffA);
;       PG8_BAR; PG8_WAIT_L(0); PG8_MMA(1, 0, At, B0); PG8_BAR; PG8_SCHED;
	s_add_u32 s50, s20, 0x20000
	s_addc_u32 s51, s21, 0
	s_add_i32 s25, s49, s31
	v_lshl_add_u64 v[130:131], s[50:51], 0, v[168:169]
	s_mov_b32 m0, s25
	s_nop 0
	global_load_lds_dwordx4 v[130:131], off
	v_lshl_add_u64 v[130:131], s[50:51], 0, v[164:165]
	s_add_i32 m0, s25, 0x2000
	s_nop 0
	global_load_lds_dwordx4 v[130:131], off
	s_waitcnt vmcnt(6)
	s_barrier
	s_setprio 1
	v_mfma_f32_16x16x32_bf16 v[54:57], v[198:201], v[146:149], v[54:57]
	v_mfma_f32_16x16x32_bf16 v[50:53], v[210:213], v[146:149], v[50:53]
	v_mfma_f32_16x16x32_bf16 v[38:41], v[198:201], v[154:157], v[38:41]
	v_mfma_f32_16x16x32_bf16 v[34:37], v[210:213], v[154:157], v[34:37]
	v_mfma_f32_16x16x32_bf16 v[22:25], v[198:201], v[178:181], v[22:25]
	v_mfma_f32_16x16x32_bf16 v[18:21], v[210:213], v[178:181], v[18:21]
	v_mfma_f32_16x16x32_bf16 v[4:7], v[198:201], v[186:189], v[4:7]
	v_mfma_f32_16x16x32_bf16 v[0:3], v[210:213], v[186:189], v[0:3]
	v_mfma_f32_16x16x32_bf16 v[54:57], v[206:209], v[150:153], v[54:57]
	v_mfma_f32_16x16x32_bf16 v[50:53], v[214:217], v[150:153], v[50:53]
	v_mfma_f32_16x16x32_bf16 v[38:41], v[206:209], v[158:161], v[38:41]
	v_mfma_f32_16x16x32_bf16 v[34:37], v[214:217], v[158:161], v[34:37]
	v_mfma_f32_16x16x32_bf16 v[22:25], v[206:209], v[182:185], v[22:25]
	v_mfma_f32_16x16x32_bf16 v[18:21], v[214:217], v[182:185], v[18:21]
	v_mfma_f32_16x16x32_bf16 v[4:7], v[206:209], v[190:193], v[4:7]
	v_mfma_f32_16x16x32_bf16 v[0:3], v[214:217], v[190:193], v[0:3]
	s_setprio 0
	s_add_i32 s25, 0, 0x18000
	v_add_u32_e32 v142, s25, v196
	s_barrier
	ds_read_b128 v[130:133], v142
	ds_read_b128 v[134:137], v142 offset:1024
	ds_read_b128 v[138:141], v142 offset:2048
	ds_read_b128 v[142:145], v142 offset:3072
	s_add_u32 s22, s22, 0x20000
	s_addc_u32 s23, s23, 0
	s_mov_b32 m0, s36
	v_lshl_add_u64 v[198:199], s[22:23], 0, v[170:171]
	ds_read_b128 v[146:149], v204 offset:32768
	ds_read_b128 v[150:153], v204 offset:33792
	ds_read_b128 v[154:157], v204 offset:34816
	ds_read_b128 v[158:161], v204 offset:35840
	ds_read_b128 v[178:181], v204 offset:36864
	ds_read_b128 v[182:185], v204 offset:37888
	ds_read_b128 v[186:189], v204 offset:38912
	ds_read_b128 v[190:193], v204 offset:39936
	global_load_lds_dwordx4 v[198:199], off
	v_lshl_add_u64 v[198:199], s[22:23], 0, v[166:167]
	s_mov_b32 m0, s37
	s_nop 0
	global_load_lds_dwordx4 v[198:199], off
	s_waitcnt lgkmcnt(8)
	s_barrier
	s_waitcnt lgkmcnt(0)
	s_setprio 1
	s_waitcnt lgkmcnt(0)
	v_mfma_f32_16x16x32_bf16 v[126:129], v[130:133], v[146:149], v[126:129]
	v_mfma_f32_16x16x32_bf16 v[122:125], v[138:141], v[146:149], v[122:125]
	v_mfma_f32_16x16x32_bf16 v[110:113], v[130:133], v[154:157], v[110:113]
	v_mfma_f32_16x16x32_bf16 v[106:109], v[138:141], v[154:157], v[106:109]
	v_mfma_f32_16x16x32_bf16 v[94:97], v[130:133], v[178:181], v[94:97]
	v_mfma_f32_16x16x32_bf16 v[90:93], v[138:141], v[178:181], v[90:93]
	v_mfma_f32_16x16x32_bf16 v[78:81], v[130:133], v[186:189], v[78:81]
	v_mfma_f32_16x16x32_bf16 v[74:77], v[138:141], v[186:189], v[74:77]
	v_mfma_f32_16x16x32_bf16 v[126:129], v[134:137], v[150:153], v[126:129]
	v_mfma_f32_16x16x32_bf16 v[122:125], v[142:145], v[150:153], v[122:125]
	v_mfma_f32_16x16x32_bf16 v[110:113], v[134:137], v[158:161], v[110:113]
	v_mfma_f32_16x16x32_bf16 v[106:109], v[142:145], v[158:161], v[106:109]
	v_mfma_f32_16x16x32_bf16 v[94:97], v[134:137], v[182:185], v[94:97]
	v_mfma_f32_16x16x32_bf16 v[90:93], v[142:145], v[182:185], v[90:93]
	v_mfma_f32_16x16x32_bf16 v[78:81], v[134:137], v[190:193], v[78:81]
	v_mfma_f32_16x16x32_bf16 v[74:77], v[142:145], v[190:193], v[74:77]
	s_setprio 0
	s_barrier
	s_add_i32 s22, 0, 0x1c000
	s_add_i32 s23, s25, s31
	v_add_u32_e32 v205, s22, v196
	v_lshl_add_u64 v[162:163], v[162:163], 0, s[16:17]
	s_mov_b32 m0, s23
	ds_read_b128 v[198:201], v205
	ds_read_b128 v[206:209], v205 offset:1024
	ds_read_b128 v[210:213], v205 offset:2048
	ds_read_b128 v[214:217], v205 offset:3072
	global_load_lds_dwordx4 v[162:163], off
	v_lshl_add_u64 v[162:163], v[194:195], 0, s[16:17]
	s_add_i32 m0, s23, 0x2000
	s_nop 0
	global_load_lds_dwordx4 v[162:163], off
	s_barrier
	s_waitcnt lgkmcnt(0)
	s_setprio 1
	s_waitcnt lgkmcnt(0)
	v_mfma_f32_16x16x32_bf16 v[118:121], v[198:201], v[146:149], v[118:121]
	v_mfma_f32_16x16x32_bf16 v[114:117], v[210:213], v[146:149], v[114:117]
	v_mfma_f32_16x16x32_bf16 v[102:105], v[198:201], v[154:157], v[102:105]
	v_mfma_f32_16x16x32_bf16 v[98:101], v[210:213], v[154:157], v[98:101]
	v_mfma_f32_16x16x32_bf16 v[86:89], v[198:201], v[178:181], v[86:89]
	v_mfma_f32_16x16x32_bf16 v[82:85], v[210:213], v[178:181], v[82:85]
	v_mfma_f32_16x16x32_bf16 v[70:73], v[198:201], v[186:189], v[70:73]
	v_mfma_f32_16x16x32_bf16 v[66:69], v[210:213], v[186:189], v[66:69]
	v_mfma_f32_16x16x32_bf16 v[118:121], v[206:209], v[150:153], v[118:121]
	v_mfma_f32_16x16x32_bf16 v[114:117], v[214:217], v[150:153], v[114:117]
	v_mfma_f32_16x16x32_bf16 v[102:105], v[206:209], v[158:161], v[102:105]
	v_mfma_f32_16x16x32_bf16 v[98:101], v[214:217], v[158:161], v[98:101]
	v_mfma_f32_16x16x32_bf16 v[86:89], v[206:209], v[182:185], v[86:89]
	v_mfma_f32_16x16x32_bf16 v[82:85], v[214:217], v[182:185], v[82:85]
	v_mfma_f32_16x16x32_bf16 v[70:73], v[206:209], v[190:193], v[70:73]
	v_mfma_f32_16x16x32_bf16 v[66:69], v[214:217], v[190:193], v[66:69]
	s_setprio 0
	s_mov_b32 m0, s42
	v_lshl_add_u64 v[162:163], v[218:219], 0, s[16:17]
	s_barrier
; #define PG8_STAGE(bufoff, gbase, voff) do { _Pragma("unroll") for (int _i = 0; _i < 2; ++_i) \
;     __builtin_amdgcn_global_load_lds((const unsigned*)((const char*)(gbase) + (voff)[_i]), (LAS unsigned*)(lds + (bufoff) + ldsw + _i * 8192), 16, 0, 0); } while (0)
; #define PG8_MMA(ai, bj, At, Bt) do { __builtin_amdgcn_s_setprio(1); _Pragma("unroll") for (int m = 0; m < 4; ++m) _Pragma("unroll") for (int n = 0; n < 2; ++n) _Pragma("unroll") for (int k = 0; k < 2; ++k) \
;     acc[ai][bj][m][n] = __builtin_amdgcn_mfma_f32_16x16x32_bf16(Bt[n][k], At[m][k], acc[ai][bj][m][n], 0, 0, 0); __builtin_amdgcn_s_setprio(0); } while (0)
; #define PG8_WAIT_V(n) asm volatile("s_waitcnt vmcnt(" #n ")" ::: "memory")
; #define PG8_WAIT_L(n) asm volatile("s_waitcnt lgkmcnt(" #n ")" ::: "memory")
; #define PG8_BAR __builtin_amdgcn_s_barrier()
; #define PG8_SCHED __builtin_amdgcn_sched_barrier(0)
; template <class Epi>
; __device__ __forceinline__ void gemm_phase(LAS unsigned char* lds, const Gemm g, const StaticOrder& S, const Epi& E) {
;     ...
;       PG8_BAR; PG8_WAIT_L(0); PG8_MMA(1, 0, At, B0); PG8_BAR; PG8_SCHED;
;       PG8_STAGE(PG8_SB(1, 1), b3 + hstepB, voffB);
;       PG8_WAIT_V(6); PG8_BAR; PG8_MMA(1, 1, At, B1); PG8_BAR;
;   __device__ __forceinline__ void operator()(const f32x4 (&acc)[2][2][4][2], const Unit& u, int wr, int wc, int fr, int fq) const {
;     const unsigned char* gate = u.which ? gb : ga;
; #pragma unroll
;     for (int ai = 0; ai < 2; ++ai) {
;       u32x2 gw[4][2];
;       u32x4 pw[4][2];
; #pragma unroll
;       for (int m = 0; m < 4; ++m)
; #pragma unroll
;         for (int bj = 0; bj < 2; ++bj) {
;           const size_t o = (size_t)(u.pm * 256 + ai * 128 + wr * 64 + m * 16 + fr) * 1024 + u.pn * 256 + bj * 128 + wc * 32 + 8 * fq;
;           gw[m][bj] = *(const u32x2*)(gate + o);
;           pw[m][bj] = (u32x4){0u, 0u, 0u, 0u};
;           if (u.which) pw[m][bj] = *(const u32x4*)(mrg + o);
	ds_read_b128 v[146:149], v204 offset:49152
	ds_read_b128 v[150:153], v204 offset:50176
	ds_read_b128 v[154:157], v204 offset:51200
	ds_read_b128 v[158:161], v204 offset:52224
	ds_read_b128 v[178:181], v204 offset:53248
	ds_read_b128 v[182:185], v204 offset:54272
	ds_read_b128 v[186:189], v204 offset:55296
	ds_read_b128 v[190:193], v204 offset:56320
	global_load_lds_dwordx4 v[162:163], off
	v_lshl_add_u64 v[162:163], v[220:221], 0, s[16:17]
	s_mov_b32 m0, s43
	s_nop 0
	global_load_lds_dwordx4 v[162:163], off
	s_barrier
	s_waitcnt lgkmcnt(0)
	s_setprio 1
	s_waitcnt lgkmcnt(0)
	v_mfma_f32_16x16x32_bf16 v[62:65], v[130:133], v[146:149], v[62:65]
	v_mfma_f32_16x16x32_bf16 v[58:61], v[138:141], v[146:149], v[58:61]
	v_mfma_f32_16x16x32_bf16 v[46:49], v[130:133], v[154:157], v[46:49]
	v_mfma_f32_16x16x32_bf16 v[42:45], v[138:141], v[154:157], v[42:45]
	v_mfma_f32_16x16x32_bf16 v[30:33], v[130:133], v[178:181], v[30:33]
	v_mfma_f32_16x16x32_bf16 v[26:29], v[138:141], v[178:181], v[26:29]
	v_mfma_f32_16x16x32_bf16 v[12:15], v[130:133], v[186:189], v[12:15]
	v_mfma_f32_16x16x32_bf16 v[8:11], v[138:141], v[186:189], v[8:11]
	v_mfma_f32_16x16x32_bf16 v[62:65], v[134:137], v[150:153], v[62:65]
	v_mfma_f32_16x16x32_bf16 v[58:61], v[142:145], v[150:153], v[58:61]
	v_mfma_f32_16x16x32_bf16 v[46:49], v[134:137], v[158:161], v[46:49]
	v_mfma_f32_16x16x32_bf16 v[42:45], v[142:145], v[158:161], v[42:45]
	v_mfma_f32_16x16x32_bf16 v[30:33], v[134:137], v[182:185], v[30:33]
	v_mfma_f32_16x16x32_bf16 v[26:29], v[142:145], v[182:185], v[26:29]
	v_mfma_f32_16x16x32_bf16 v[12:15], v[134:137], v[190:193], v[12:15]
	v_mfma_f32_16x16x32_bf16 v[8:11], v[142:145], v[190:193], v[8:11]
	s_setprio 0
	s_barrier
	s_add_u32 s20, s20, 0x20080
	s_addc_u32 s21, s21, 0
	s_add_i32 s22, s22, s31
	v_lshl_add_u64 v[130:131], s[20:21], 0, v[168:169]
	s_mov_b32 m0, s22
	s_nop 0
	global_load_lds_dwordx4 v[130:131], off
	v_lshl_add_u64 v[130:131], s[20:21], 0, v[164:165]
	s_add_i32 m0, s22, 0x2000
	s_nop 0
	global_load_lds_dwordx4 v[130:131], off
	s_waitcnt vmcnt(6)
	s_barrier
	s_setprio 1
	v_mfma_f32_16x16x32_bf16 v[54:57], v[198:201], v[146:149], v[54:57]
	v_mfma_f32_16x16x32_bf16 v[50:53], v[210:213], v[146:149], v[50:53]
	v_mfma_f32_16x16x32_bf16 v[38:41], v[198:201], v[154:157], v[38:41]
	v_mfma_f32_16x16x32_bf16 v[34:37], v[210:213], v[154:157], v[34:37]
	v_mfma_f32_16x16x32_bf16 v[22:25], v[198:201], v[178:181], v[22:25]
	v_mfma_f32_16x16x32_bf16 v[18:21], v[210:213], v[178:181], v[18:21]
	v_mfma_f32_16x16x32_bf16 v[4:7], v[198:201], v[186:189], v[4:7]
	v_mfma_f32_16x16x32_bf16 v[0:3], v[210:213], v[186:189], v[0:3]
	v_mfma_f32_16x16x32_bf16 v[54:57], v[206:209], v[150:153], v[54:57]
	v_mfma_f32_16x16x32_bf16 v[50:53], v[214:217], v[150:153], v[50:53]
	v_mfma_f32_16x16x32_bf16 v[38:41], v[206:209], v[158:161], v[38:41]
	v_mfma_f32_16x16x32_bf16 v[34:37], v[214:217], v[158:161], v[34:37]
	v_mfma_f32_16x16x32_bf16 v[22:25], v[206:209], v[182:185], v[22:25]
	v_mfma_f32_16x16x32_bf16 v[18:21], v[214:217], v[182:185], v[18:21]
	v_mfma_f32_16x16x32_bf16 v[4:7], v[206:209], v[190:193], v[4:7]
	v_mfma_f32_16x16x32_bf16 v[0:3], v[214:217], v[190:193], v[0:3]
	s_setprio 0
	s_add_i32 s24, s24, 2
	s_add_u32 s0, s0, 0x100
	s_addc_u32 s1, s1, 0
	s_add_u32 s7, s7, 0x100
	s_addc_u32 s9, s9, 0
	s_cmp_gt_u32 s24, 5
	s_barrier
	s_cbranch_scc0 .LBB0_3542
	s_cmp_lg_u32 s48, 0
	s_cselect_b64 s[24:25], -1, 0
	s_cmp_eq_u32 s48, 0
	s_cselect_b64 s[0:1], -1, 0
	s_and_b64 vcc, s[0:1], exec
	s_mov_b32 s0, 0x10922000
	s_cselect_b32 s0, s0, 0x14a22000
	s_add_u32 s22, s2, s0
	s_addc_u32 s23, s3, 0
	s_lshl_b32 s7, s47, 8
	v_add_u32_e32 v178, s7, v173
	s_lshl_b32 s20, s46, 8
	s_ashr_i32 s21, s20, 31
	v_ashrrev_i32_e32 v179, 31, v178
	v_mov_b32_e32 v181, s21
	v_or_b32_e32 v180, s20, v172
	v_lshlrev_b64 v[130:131], 10, v[178:179]
	v_lshl_add_u64 v[130:131], v[130:131], 0, v[180:181]
	v_lshl_add_u64 v[132:133], s[22:23], 0, v[130:131]
	global_load_dwordx2 v[198:199], v[132:133], off
	v_add_u32_e32 v238, 0x80, v178
	v_mov_b32_e32 v240, v238
	v_ashrrev_i32_e32 v241, 31, v240
	v_lshlrev_b64 v[240:241], 10, v[240:241]
	v_lshl_add_u64 v[240:241], v[240:241], 0, v[180:181]
	v_lshl_add_u64 v[240:241], s[22:23], 0, v[240:241]
	global_load_dwordx2 v[222:223], v[240:241], off
	global_load_dwordx2 v[224:225], v[240:241], off offset:128
	v_or_b32_e32 v240, 16, v238
	v_ashrrev_i32_e32 v241, 31, v240
	v_lshlrev_b64 v[240:241], 10, v[240:241]
	v_lshl_add_u64 v[240:241], v[240:241], 0, v[180:181]
	v_lshl_add_u64 v[240:241], s[22:23], 0, v[240:241]
	global_load_dwordx2 v[226:227], v[240:241], off
	global_load_dwordx2 v[228:229], v[240:241], off offset:128
	v_or_b32_e32 v240, 32, v238
	v_ashrrev_i32_e32 v241, 31, v240
	v_lshlrev_b64 v[240:241], 10, v[240:241]
	v_lshl_add_u64 v[240:241], v[240:241], 0, v[180:181]
	v_lshl_add_u64 v[240:241], s[22:23], 0, v[240:241]
	global_load_dwordx2 v[230:231], v[240:241], off
	global_load_dwordx2 v[232:233], v[240:241], off offset:128
	v_or_b32_e32 v240, 48, v238
	v_ashrrev_i32_e32 v241, 31, v240
	v_lshlrev_b64 v[240:241], 10, v[240:241]
	v_lshl_add_u64 v[240:241], v[240:241], 0, v[180:181]
	v_lshl_add_u64 v[240:241], s[22:23], 0, v[240:241]
	global_load_dwordx2 v[234:235], v[240:241], off
	global_load_dwordx2 v[236:237], v[240:241], off offset:128
	v_mov_b32_e32 v148, 0
	v_mov_b32_e32 v160, 0
	v_mov_b32_e32 v161, 0
	v_mov_b32_e32 v162, 0
	v_mov_b32_e32 v163, 0
	s_cbranch_vccnz .LBB0_3545
	v_lshl_add_u64 v[134:135], v[130:131], 1, s[4:5]
	global_load_dwordx4 v[160:163], v[134:135], off

; __device__ __forceinline__ float bflo(unsigned w) { return __uint_as_float(w << 16); }
; __device__ __forceinline__ float bfhi(unsigned w) { return __uint_as_float(w & 0xffff0000u); }
;   __device__ __forceinline__ void operator()(const f32x4 (&acc)[2][2][4][2], const Unit& u, int wr, int wc, int fr, int fq) const {
;     ...
; #pragma unroll
;       for (int m = 0; m < 4; ++m)
; #pragma unroll
;         for (int bj = 0; bj < 2; ++bj) {
;           const size_t o = (size_t)(u.pm * 256 + ai * 128 + wr * 64 + m * 16 + fr) * 1024 + u.pn * 256 + bj * 128 + wc * 32 + 8 * fq;
;           float v[8];
; #pragma unroll
;           for (int e = 0; e < 8; ++e) v[e] = (float)((gw[m][bj][e >> 2] >> (8 * (e & 3))) & 0xffu) * (1.f / 255.f) * acc[ai][bj][m][e >> 2][e & 3];
; #pragma unroll
;           for (int e = 0; e < 4; ++e) { v[2 * e] += bflo(pw[m][bj][e]); v[2 * e + 1] += bfhi(pw[m][bj][e]); }
;           u32x4 w;
; #pragma unroll
;           for (int e = 0; e < 4; ++e) w[e] = cvt_pk_bf16(v[2 * e], v[2 * e + 1]);
;           *(u32x4*)(mrg + o) = w;
;         }
.LBB0_3559:
	s_waitcnt vmcnt(0)
	v_cvt_f32_ubyte0_e32 v131, v198
	v_mul_f32_e32 v131, 0x3b808081, v131
	v_cvt_f32_ubyte1_e32 v200, v198
	v_lshlrev_b32_e32 v208, 16, v160
	v_mul_f32_e32 v200, 0x3b808081, v200
	v_cvt_f32_ubyte2_e32 v201, v198
	v_fmac_f32_e32 v208, v126, v131
	v_and_b32_e32 v126, 0xffff0000, v160
	v_mul_f32_e32 v201, 0x3b808081, v201
	v_cvt_f32_ubyte3_e32 v198, v198
	v_fmac_f32_e32 v126, v127, v200
	v_lshlrev_b32_e32 v127, 16, v161
	v_mul_f32_e32 v198, 0x3b808081, v198
	v_cvt_f32_ubyte0_e32 v205, v199
	v_cvt_f32_ubyte1_e32 v206, v199
	v_fmac_f32_e32 v127, v128, v201
	v_and_b32_e32 v128, 0xffff0000, v161
	v_mul_f32_e32 v205, 0x3b808081, v205
	v_mul_f32_e32 v206, 0x3b808081, v206
	v_fmac_f32_e32 v128, v129, v198
	v_lshlrev_b32_e32 v129, 16, v162
	v_and_b32_e32 v131, 0xffff0000, v162
	v_fmac_f32_e32 v129, v122, v205
	v_fmac_f32_e32 v131, v123, v206
	v_cvt_pk_bf16_f32 v122, v208, v126
	v_cvt_pk_bf16_f32 v123, v127, v128
	v_lshlrev_b64 v[126:127], 11, v[178:179]
	v_lshl_add_u64 v[126:127], s[4:5], 0, v[126:127]
	s_lshl_b64 s[20:21], s[20:21], 1
	v_readlane_b32 s24, v255, 20
	v_lshl_add_u64 v[126:127], v[126:127], 0, s[20:21]
	v_readlane_b32 s25, v255, 21
	v_cvt_f32_ubyte2_e32 v207, v199
	v_cvt_f32_ubyte3_e32 v199, v199
	v_lshl_add_u64 v[126:127], v[126:127], 0, s[24:25]
	v_mul_f32_e32 v207, 0x3b808081, v207
	v_mul_f32_e32 v199, 0x3b808081, v199
	v_lshlrev_b32_e32 v160, 16, v163
	v_and_b32_e32 v161, 0xffff0000, v163
	v_lshl_add_u64 v[126:127], v[126:127], 0, v[16:17]
	v_fmac_f32_e32 v160, v124, v207
	v_fmac_f32_e32 v161, v125, v199
	v_cvt_pk_bf16_f32 v124, v129, v131
	v_cvt_pk_bf16_f32 v125, v160, v161
	global_store_dwordx4 v[126:127], v[122:125], off
	v_lshlrev_b32_e32 v161, 16, v156
	v_cvt_f32_ubyte0_e32 v128, v195
	v_cvt_f32_ubyte0_e32 v122, v194
	v_mul_f32_e32 v122, 0x3b808081, v122
	v_cvt_f32_ubyte1_e32 v123, v194
	v_mul_f32_e32 v123, 0x3b808081, v123
	v_cvt_f32_ubyte2_e32 v124, v194
	v_fmac_f32_e32 v161, v118, v122
	v_and_b32_e32 v118, 0xffff0000, v156
	v_mul_f32_e32 v124, 0x3b808081, v124
	v_cvt_f32_ubyte3_e32 v125, v194
	v_fmac_f32_e32 v118, v119, v123
	v_lshlrev_b32_e32 v119, 16, v157
	v_mul_f32_e32 v125, 0x3b808081, v125
	v_cvt_f32_ubyte1_e32 v129, v195
	v_fmac_f32_e32 v119, v120, v124
	v_and_b32_e32 v120, 0xffff0000, v157
	v_mul_f32_e32 v128, 0x3b808081, v128
	v_mul_f32_e32 v129, 0x3b808081, v129
	v_cvt_f32_ubyte2_e32 v131, v195
	v_cvt_f32_ubyte3_e32 v160, v195
	v_fmac_f32_e32 v120, v121, v125
	v_lshlrev_b32_e32 v121, 16, v158
	v_and_b32_e32 v122, 0xffff0000, v158
	v_mul_f32_e32 v131, 0x3b808081, v131
	v_mul_f32_e32 v160, 0x3b808081, v160
	v_fmac_f32_e32 v121, v114, v128
	v_fmac_f32_e32 v122, v115, v129
	v_lshlrev_b32_e32 v123, 16, v159
	v_and_b32_e32 v124, 0xffff0000, v159
	v_cvt_pk_bf16_f32 v114, v161, v118
	v_cvt_pk_bf16_f32 v115, v119, v120
	v_fmac_f32_e32 v123, v116, v131
	v_fmac_f32_e32 v124, v117, v160
	v_cvt_pk_bf16_f32 v116, v121, v122
	v_cvt_pk_bf16_f32 v117, v123, v124
	global_store_dwordx4 v[126:127], v[114:117], off offset:256
	v_lshlrev_b32_e32 v123, 16, v148
	v_cvt_f32_ubyte3_e32 v118, v192
	v_cvt_f32_ubyte0_e32 v115, v192
	v_mul_f32_e32 v115, 0x3b808081, v115
	v_cvt_f32_ubyte1_e32 v116, v192
	v_mul_f32_e32 v116, 0x3b808081, v116
	v_cvt_f32_ubyte2_e32 v117, v192
	v_fmac_f32_e32 v123, v110, v115
	v_and_b32_e32 v110, 0xffff0000, v148
	v_mul_f32_e32 v117, 0x3b808081, v117
	v_fmac_f32_e32 v110, v111, v116
	v_lshlrev_b32_e32 v111, 16, v149
	v_add_u32_e32 v114, s7, v197
	v_mul_f32_e32 v118, 0x3b808081, v118
	v_cvt_f32_ubyte0_e32 v119, v193
	v_cvt_f32_ubyte1_e32 v120, v193
	v_fmac_f32_e32 v111, v112, v117
	v_and_b32_e32 v112, 0xffff0000, v149
	v_mul_f32_e32 v119, 0x3b808081, v119
	v_mul_f32_e32 v120, 0x3b808081, v120
	v_fmac_f32_e32 v112, v113, v118
	v_lshlrev_b32_e32 v113, 16, v150
	v_and_b32_e32 v116, 0xffff0000, v150
	v_ashrrev_i32_e32 v115, 31, v114
	v_fmac_f32_e32 v113, v106, v119
	v_fmac_f32_e32 v116, v107, v120
	v_cvt_pk_bf16_f32 v106, v123, v110
	v_cvt_pk_bf16_f32 v107, v111, v112
	v_lshlrev_b64 v[110:111], 11, v[114:115]
	v_lshl_add_u64 v[110:111], s[4:5], 0, v[110:111]
	v_lshl_add_u64 v[110:111], v[110:111], 0, s[20:21]
	v_cvt_f32_ubyte2_e32 v121, v193
	v_cvt_f32_ubyte3_e32 v122, v193
	v_lshl_add_u64 v[110:111], v[110:111], 0, s[24:25]
	v_mul_f32_e32 v121, 0x3b808081, v121
	v_mul_f32_e32 v122, 0x3b808081, v122
	v_lshlrev_b32_e32 v117, 16, v151
	v_and_b32_e32 v118, 0xffff0000, v151
	v_lshl_add_u64 v[110:111], v[110:111], 0, v[16:17]
	v_fmac_f32_e32 v117, v108, v121
	v_fmac_f32_e32 v118, v109, v122
	v_cvt_pk_bf16_f32 v108, v113, v116
	v_cvt_pk_bf16_f32 v109, v117, v118
	global_store_dwordx4 v[110:111], v[106:109], off
	v_lshlrev_b32_e32 v116, 16, v152
	v_cvt_f32_ubyte0_e32 v112, v191
	v_cvt_f32_ubyte0_e32 v106, v190
	v_mul_f32_e32 v106, 0x3b808081, v106
	v_cvt_f32_ubyte1_e32 v107, v190
	v_mul_f32_e32 v107, 0x3b808081, v107
	v_cvt_f32_ubyte2_e32 v108, v190
	v_fmac_f32_e32 v116, v102, v106
	v_and_b32_e32 v102, 0xffff0000, v152
	v_mul_f32_e32 v108, 0x3b808081, v108
	v_cvt_f32_ubyte3_e32 v109, v190
	v_fmac_f32_e32 v102, v103, v107
	v_lshlrev_b32_e32 v103, 16, v153
	v_mul_f32_e32 v109, 0x3b808081, v109
	v_cvt_f32_ubyte1_e32 v113, v191
	v_fmac_f32_e32 v103, v104, v108
	v_and_b32_e32 v104, 0xffff0000, v153
	v_mul_f32_e32 v112, 0x3b808081, v112
	v_mul_f32_e32 v113, 0x3b808081, v113
	v_cvt_f32_ubyte2_e32 v114, v191
	v_cvt_f32_ubyte3_e32 v115, v191
	v_fmac_f32_e32 v104, v105, v109
	v_lshlrev_b32_e32 v105, 16, v154
	v_and_b32_e32 v106, 0xffff0000, v154
	v_mul_f32_e32 v114, 0x3b808081, v114
	v_mul_f32_e32 v115, 0x3b808081, v115
	v_fmac_f32_e32 v105, v98, v112
	v_fmac_f32_e32 v106, v99, v113
	v_lshlrev_b32_e32 v107, 16, v155
; __device__ __forceinline__ float bflo(unsigned w) { return __uint_as_float(w << 16); }
; __device__ __forceinline__ float bfhi(unsigned w) { return __uint_as_float(w & 0xffff0000u); }
;   __device__ __forceinline__ void operator()(const f32x4 (&acc)[2][2][4][2], const Unit& u, int wr, int wc, int fr, int fq) const {
;     ...
;       for (int m = 0; m < 4; ++m)
; #pragma unroll
;         for (int bj = 0; bj < 2; ++bj) {
;           const size_t o = (size_t)(u.pm * 256 + ai * 128 + wr * 64 + m * 16 + fr) * 1024 + u.pn * 256 + bj * 128 + wc * 32 + 8 * fq;
;           gw[m][bj] = *(const u32x2*)(gate + o);
;           pw[m][bj] = (u32x4){0u, 0u, 0u, 0u};
;           if (u.which) pw[m][bj] = *(const u32x4*)(mrg + o);
;     ...
; #pragma unroll
;       for (int m = 0; m < 4; ++m)
; #pragma unroll
;         for (int bj = 0; bj < 2; ++bj) {
;           const size_t o = (size_t)(u.pm * 256 + ai * 128 + wr * 64 + m * 16 + fr) * 1024 + u.pn * 256 + bj * 128 + wc * 32 + 8 * fq;
;           float v[8];
; #pragma unroll
;           for (int e = 0; e < 8; ++e) v[e] = (float)((gw[m][bj][e >> 2] >> (8 * (e & 3))) & 0xffu) * (1.f / 255.f) * acc[ai][bj][m][e >> 2][e & 3];
; #pragma unroll
;           for (int e = 0; e < 4; ++e) { v[2 * e] += bflo(pw[m][bj][e]); v[2 * e + 1] += bfhi(pw[m][bj][e]); }
;           u32x4 w;
; #pragma unroll
;           for (int e = 0; e < 4; ++e) w[e] = cvt_pk_bf16(v[2 * e], v[2 * e + 1]);
;           *(u32x4*)(mrg + o) = w;
;         }
	v_and_b32_e32 v108, 0xffff0000, v155
	v_cvt_pk_bf16_f32 v98, v116, v102
	v_cvt_pk_bf16_f32 v99, v103, v104
	v_fmac_f32_e32 v107, v100, v114
	v_fmac_f32_e32 v108, v101, v115
	v_cvt_pk_bf16_f32 v100, v105, v106
	v_cvt_pk_bf16_f32 v101, v107, v108
	global_store_dwordx4 v[110:111], v[98:101], off offset:256
	v_lshlrev_b32_e32 v107, 16, v140
	v_cvt_f32_ubyte3_e32 v102, v188
	v_cvt_f32_ubyte0_e32 v99, v188
	v_mul_f32_e32 v99, 0x3b808081, v99
	v_cvt_f32_ubyte1_e32 v100, v188
	v_mul_f32_e32 v100, 0x3b808081, v100
	v_cvt_f32_ubyte2_e32 v101, v188
	v_fmac_f32_e32 v107, v94, v99
	v_and_b32_e32 v94, 0xffff0000, v140
	v_mul_f32_e32 v101, 0x3b808081, v101
	v_fmac_f32_e32 v94, v95, v100
	v_lshlrev_b32_e32 v95, 16, v141
	v_add_u32_e32 v98, s7, v202
	v_mul_f32_e32 v102, 0x3b808081, v102
	v_cvt_f32_ubyte0_e32 v103, v189
	v_cvt_f32_ubyte1_e32 v104, v189
	v_fmac_f32_e32 v95, v96, v101
	v_and_b32_e32 v96, 0xffff0000, v141
	v_mul_f32_e32 v103, 0x3b808081, v103
	v_mul_f32_e32 v104, 0x3b808081, v104
	v_fmac_f32_e32 v96, v97, v102
	v_lshlrev_b32_e32 v97, 16, v142
	v_and_b32_e32 v100, 0xffff0000, v142
	v_ashrrev_i32_e32 v99, 31, v98
	v_fmac_f32_e32 v97, v90, v103
	v_fmac_f32_e32 v100, v91, v104
	v_cvt_pk_bf16_f32 v90, v107, v94
	v_cvt_pk_bf16_f32 v91, v95, v96
	v_lshlrev_b64 v[94:95], 11, v[98:99]
	v_lshl_add_u64 v[94:95], s[4:5], 0, v[94:95]
	v_lshl_add_u64 v[94:95], v[94:95], 0, s[20:21]
	v_cvt_f32_ubyte2_e32 v105, v189
	v_cvt_f32_ubyte3_e32 v106, v189
	v_lshl_add_u64 v[94:95], v[94:95], 0, s[24:25]
	v_mul_f32_e32 v105, 0x3b808081, v105
	v_mul_f32_e32 v106, 0x3b808081, v106
	v_lshlrev_b32_e32 v101, 16, v143
	v_and_b32_e32 v102, 0xffff0000, v143
	v_lshl_add_u64 v[94:95], v[94:95], 0, v[16:17]
	v_fmac_f32_e32 v101, v92, v105
	v_fmac_f32_e32 v102, v93, v106
	v_cvt_pk_bf16_f32 v92, v97, v100
	v_cvt_pk_bf16_f32 v93, v101, v102
	global_store_dwordx4 v[94:95], v[90:93], off
	v_lshlrev_b32_e32 v100, 16, v144
	v_cvt_f32_ubyte0_e32 v96, v187
	v_cvt_f32_ubyte0_e32 v90, v186
	v_mul_f32_e32 v90, 0x3b808081, v90
	v_cvt_f32_ubyte1_e32 v91, v186
	v_mul_f32_e32 v91, 0x3b808081, v91
	v_cvt_f32_ubyte2_e32 v92, v186
	v_fmac_f32_e32 v100, v86, v90
	v_and_b32_e32 v86, 0xffff0000, v144
	v_mul_f32_e32 v92, 0x3b808081, v92
	v_cvt_f32_ubyte3_e32 v93, v186
	v_fmac_f32_e32 v86, v87, v91
	v_lshlrev_b32_e32 v87, 16, v145
	v_mul_f32_e32 v93, 0x3b808081, v93
	v_cvt_f32_ubyte1_e32 v97, v187
	v_fmac_f32_e32 v87, v88, v92
	v_and_b32_e32 v88, 0xffff0000, v145
	v_mul_f32_e32 v96, 0x3b808081, v96
	v_mul_f32_e32 v97, 0x3b808081, v97
	v_cvt_f32_ubyte2_e32 v98, v187
	v_cvt_f32_ubyte3_e32 v99, v187
	v_fmac_f32_e32 v88, v89, v93
	v_lshlrev_b32_e32 v89, 16, v146
	v_and_b32_e32 v90, 0xffff0000, v146
	v_mul_f32_e32 v98, 0x3b808081, v98
	v_mul_f32_e32 v99, 0x3b808081, v99
	v_fmac_f32_e32 v89, v82, v96
	v_fmac_f32_e32 v90, v83, v97
	v_lshlrev_b32_e32 v91, 16, v147
	v_and_b32_e32 v92, 0xffff0000, v147
	v_cvt_pk_bf16_f32 v82, v100, v86
	v_cvt_pk_bf16_f32 v83, v87, v88
	v_fmac_f32_e32 v91, v84, v98
	v_fmac_f32_e32 v92, v85, v99
	v_cvt_pk_bf16_f32 v84, v89, v90
	v_cvt_pk_bf16_f32 v85, v91, v92
	global_store_dwordx4 v[94:95], v[82:85], off offset:256
	v_lshlrev_b32_e32 v91, 16, v132
	v_cvt_f32_ubyte3_e32 v86, v184
	v_cvt_f32_ubyte0_e32 v83, v184
	v_mul_f32_e32 v83, 0x3b808081, v83
	v_cvt_f32_ubyte1_e32 v84, v184
	v_mul_f32_e32 v84, 0x3b808081, v84
	v_cvt_f32_ubyte2_e32 v85, v184
	v_fmac_f32_e32 v91, v78, v83
	v_and_b32_e32 v78, 0xffff0000, v132
	v_mul_f32_e32 v85, 0x3b808081, v85
	v_fmac_f32_e32 v78, v79, v84
	v_lshlrev_b32_e32 v79, 16, v133
	v_add_u32_e32 v82, s7, v203
	v_mul_f32_e32 v86, 0x3b808081, v86
	v_cvt_f32_ubyte0_e32 v87, v185
	v_cvt_f32_ubyte1_e32 v88, v185
	v_fmac_f32_e32 v79, v80, v85
	v_and_b32_e32 v80, 0xffff0000, v133
	v_mul_f32_e32 v87, 0x3b808081, v87
	v_mul_f32_e32 v88, 0x3b808081, v88
	v_fmac_f32_e32 v80, v81, v86
	v_lshlrev_b32_e32 v81, 16, v134
	v_and_b32_e32 v84, 0xffff0000, v134
	v_ashrrev_i32_e32 v83, 31, v82
	v_fmac_f32_e32 v81, v74, v87
	v_fmac_f32_e32 v84, v75, v88
	v_cvt_pk_bf16_f32 v74, v91, v78
	v_cvt_pk_bf16_f32 v75, v79, v80
	v_lshlrev_b64 v[78:79], 11, v[82:83]
	v_lshl_add_u64 v[78:79], s[4:5], 0, v[78:79]
	v_lshl_add_u64 v[78:79], v[78:79], 0, s[20:21]
	v_cvt_f32_ubyte2_e32 v89, v185
	v_cvt_f32_ubyte3_e32 v90, v185
	v_lshl_add_u64 v[78:79], v[78:79], 0, s[24:25]
	v_mul_f32_e32 v89, 0x3b808081, v89
	v_mul_f32_e32 v90, 0x3b808081, v90
	v_lshlrev_b32_e32 v85, 16, v135
	v_and_b32_e32 v86, 0xffff0000, v135
	v_lshl_add_u64 v[78:79], v[78:79], 0, v[16:17]
	v_fmac_f32_e32 v85, v76, v89
	v_fmac_f32_e32 v86, v77, v90
	v_cvt_pk_bf16_f32 v76, v81, v84
	v_cvt_pk_bf16_f32 v77, v85, v86
	global_store_dwordx4 v[78:79], v[74:77], off
	v_lshlrev_b32_e32 v84, 16, v136
	v_cvt_f32_ubyte0_e32 v80, v183
	v_cvt_f32_ubyte0_e32 v74, v182
	v_mul_f32_e32 v74, 0x3b808081, v74
	v_cvt_f32_ubyte1_e32 v75, v182
	v_mul_f32_e32 v75, 0x3b808081, v75
	v_cvt_f32_ubyte2_e32 v76, v182
	v_fmac_f32_e32 v84, v70, v74
	v_and_b32_e32 v70, 0xffff0000, v136
	v_mul_f32_e32 v76, 0x3b808081, v76
	v_cvt_f32_ubyte3_e32 v77, v182
	v_fmac_f32_e32 v70, v71, v75
	v_lshlrev_b32_e32 v71, 16, v137
	v_mul_f32_e32 v77, 0x3b808081, v77
	v_cvt_f32_ubyte1_e32 v81, v183
	v_fmac_f32_e32 v71, v72, v76
	v_and_b32_e32 v72, 0xffff0000, v137
	v_mul_f32_e32 v80, 0x3b808081, v80
	v_mul_f32_e32 v81, 0x3b808081, v81
	v_cvt_f32_ubyte2_e32 v82, v183
	v_cvt_f32_ubyte3_e32 v83, v183
	v_fmac_f32_e32 v72, v73, v77
	v_lshlrev_b32_e32 v73, 16, v138
	v_and_b32_e32 v74, 0xffff0000, v138
	v_add_u32_e32 v106, 0x80, v178
	v_mul_f32_e32 v82, 0x3b808081, v82
	v_mul_f32_e32 v83, 0x3b808081, v83
	v_fmac_f32_e32 v73, v66, v80
	v_fmac_f32_e32 v74, v67, v81
	v_lshlrev_b32_e32 v75, 16, v139
	v_and_b32_e32 v76, 0xffff0000, v139
	v_cvt_pk_bf16_f32 v66, v84, v70
	v_cvt_pk_bf16_f32 v67, v71, v72
	v_ashrrev_i32_e32 v107, 31, v106
	v_fmac_f32_e32 v75, v68, v82
	v_fmac_f32_e32 v76, v69, v83
	v_cvt_pk_bf16_f32 v68, v73, v74
	v_cvt_pk_bf16_f32 v69, v75, v76
	global_store_dwordx4 v[78:79], v[66:69], off offset:256
	s_and_b64 vcc, exec, s[0:1]
	v_mov_b32_e32 v131, 0
	v_lshlrev_b64 v[66:67], 10, v[106:107]
	v_lshl_add_u64 v[66:67], v[66:67], 0, v[180:181]
	v_lshl_add_u64 v[68:69], s[22:23], 0, v[66:67]
	v_mov_b32_e32 v132, 0
	v_mov_b32_e32 v133, 0
	s_cbranch_vccnz .LBB0_3561
	v_lshl_add_u64 v[70:71], v[66:67], 1, s[4:5]
	global_load_dwordx4 v[130:133], v[70:71], off
;   __device__ __forceinline__ void operator()(const f32x4 (&acc)[2][2][4][2], const Unit& u, int wr, int wc, int fr, int fq) const {
;     ...
;       for (int m = 0; m < 4; ++m)
; #pragma unroll
;         for (int bj = 0; bj < 2; ++bj) {
;           const size_t o = (size_t)(u.pm * 256 + ai * 128 + wr * 64 + m * 16 + fr) * 1024 + u.pn * 256 + bj * 128 + wc * 32 + 8 * fq;
;           gw[m][bj] = *(const u32x2*)(gate + o);
;           pw[m][bj] = (u32x4){0u, 0u, 0u, 0u};
;           if (u.which) pw[m][bj] = *(const u32x4*)(mrg + o);
.LBB0_3561:
	v_mov_b32_e32 v82, 0
	s_and_b64 vcc, exec, s[0:1]
	v_mov_b32_e32 v90, 0
	v_mov_b32_e32 v91, 0
	v_mov_b32_e32 v92, 0
	v_mov_b32_e32 v93, 0
	s_cbranch_vccnz .LBB0_3563
	v_lshlrev_b64 v[66:67], 1, v[66:67]
	v_or_b32_e32 v66, 0x100, v66
	v_lshl_add_u64 v[66:67], s[4:5], 0, v[66:67]
	global_load_dwordx4 v[90:93], v[66:67], off
.LBB0_3563:
	v_or_b32_e32 v66, 16, v106
	v_ashrrev_i32_e32 v67, 31, v66
	v_lshlrev_b64 v[66:67], 10, v[66:67]
	v_lshl_add_u64 v[66:67], v[66:67], 0, v[180:181]
	v_lshl_add_u64 v[68:69], s[22:23], 0, v[66:67]
	s_and_b64 vcc, exec, s[0:1]
	v_mov_b32_e32 v83, 0
	v_mov_b32_e32 v84, 0
	v_mov_b32_e32 v85, 0
	s_cbranch_vccnz .LBB0_3565
	v_lshl_add_u64 v[70:71], v[66:67], 1, s[4:5]
	global_load_dwordx4 v[82:85], v[70:71], off
.LBB0_3565:
	v_mov_b32_e32 v74, 0
	s_and_b64 vcc, exec, s[0:1]
	v_mov_b32_e32 v86, 0
	v_mov_b32_e32 v87, 0
	v_mov_b32_e32 v88, 0
	v_mov_b32_e32 v89, 0
	s_cbranch_vccnz .LBB0_3567
	v_lshlrev_b64 v[66:67], 1, v[66:67]
	v_or_b32_e32 v66, 0x100, v66
	v_lshl_add_u64 v[66:67], s[4:5], 0, v[66:67]
	global_load_dwordx4 v[86:89], v[66:67], off
.LBB0_3567:
	v_or_b32_e32 v66, 32, v106
	v_ashrrev_i32_e32 v67, 31, v66
	v_lshlrev_b64 v[66:67], 10, v[66:67]
	v_lshl_add_u64 v[68:69], v[66:67], 0, v[180:181]
	v_lshl_add_u64 v[66:67], s[22:23], 0, v[68:69]
	s_and_b64 vcc, exec, s[0:1]
	v_mov_b32_e32 v75, 0
	v_mov_b32_e32 v76, 0
	v_mov_b32_e32 v77, 0
	s_cbranch_vccnz .LBB0_3569
	v_lshl_add_u64 v[70:71], v[68:69], 1, s[4:5]
	global_load_dwordx4 v[74:77], v[70:71], off
.LBB0_3569:
	v_mov_b32_e32 v66, 0
	s_and_b64 vcc, exec, s[0:1]
	v_mov_b32_e32 v78, 0
	v_mov_b32_e32 v79, 0
	v_mov_b32_e32 v80, 0
	v_mov_b32_e32 v81, 0
	s_cbranch_vccnz .LBB0_3571
	v_lshlrev_b64 v[68:69], 1, v[68:69]
	v_or_b32_e32 v68, 0x100, v68
	v_lshl_add_u64 v[68:69], s[4:5], 0, v[68:69]
	global_load_dwordx4 v[78:81], v[68:69], off
.LBB0_3571:
	v_or_b32_e32 v68, 48, v106
	v_ashrrev_i32_e32 v69, 31, v68
	v_lshlrev_b64 v[68:69], 10, v[68:69]
	v_lshl_add_u64 v[112:113], v[68:69], 0, v[180:181]
	v_lshl_add_u64 v[70:71], s[22:23], 0, v[112:113]
	s_and_b64 vcc, exec, s[0:1]
	v_mov_b32_e32 v67, 0
	v_mov_b32_e32 v68, 0
	v_mov_b32_e32 v69, 0
	s_cbranch_vccnz .LBB0_3573
	v_lshl_add_u64 v[66:67], v[112:113], 1, s[4:5]
	global_load_dwordx4 v[66:69], v[66:67], off
.LBB0_3573:
	s_nop 0
	v_mov_b32_e32 v70, 0
	s_and_b64 vcc, exec, s[0:1]
	v_mov_b32_e32 v71, 0
	v_mov_b32_e32 v72, 0
	v_mov_b32_e32 v73, 0
	s_cbranch_vccnz .LBB0_3528
	v_lshlrev_b64 v[70:71], 1, v[112:113]
	v_or_b32_e32 v70, 0x100, v70
	v_lshl_add_u64 v[70:71], s[4:5], 0, v[70:71]
	global_load_dwordx4 v[70:73], v[70:71], off
	s_branch .LBB0_3528
